# phase-0 modulation GEMV: next batch weight-row loads issued before current batch FMAs (double-buffered), on top of v4
# baseline (speedup 1.0000x reference)
; template <int ph> __device__ __forceinline__ void run_phase(const MArgs& a, unsigned char* lds, int tid, int lane, int wave, int G, int bx, int vcu) {
;     ...
;       for (int i = tid; i < 17 * 1024; i += NWAVES * 64) { const int r = i >> 10, k = i & 1023; const float v = r < 16 ? a.in[1][r * 1024 + k] : a.in[3][k]; cond[i] = v / (1.f + __expf(-v)); }
;       __syncthreads();
;       const int l = bx / 96, cc = bx % 96; const float* W = a.in[4] + (size_t)l * 1024 * 6144 + cc * 64 + lane;
;       float acc[17];
; #pragma unroll
;       for (int r = 0; r < 17; ++r) acc[r] = 0.f;
;       for (int k0 = wave * 128; k0 < wave * 128 + 128; k0 += 16) { float wv[16];
; #pragma unroll
;         for (int q = 0; q < 16; ++q) wv[q] = W[(size_t)(k0 + q) * 6144];
; #pragma unroll
;         for (int q = 0; q < 16; ++q)
; #pragma unroll
;           for (int r = 0; r < 17; ++r) acc[r] += cond[r * 1024 + k0 + q] * wv[q]; }
.LBB0_22:
	v_and_b32_e32 v2, 0x3ff, v6
	v_lshlrev_b32_e32 v2, 2, v2
	v_lshl_add_u64 v[8:9], s[58:59], 0, v[2:3]
	v_cmp_gt_u32_e32 vcc, s3, v6
	v_add_u32_e32 v7, 0x200, v6
	s_nop 0
	v_cndmask_b32_e32 v9, v9, v5, vcc
	v_cndmask_b32_e32 v8, v8, v4, vcc
	global_load_dword v2, v[8:9], off
	v_cmp_lt_u32_e32 vcc, s6, v6
	v_mov_b32_e32 v6, v7
	s_or_b64 s[0:1], vcc, s[0:1]
	v_lshl_add_u64 v[4:5], v[4:5], 0, s[4:5]
	s_waitcnt vmcnt(0)
	v_mul_f32_e32 v7, 0xbfb8aa3b, v2
	v_exp_f32_e32 v7, v7
	s_nop 0
	v_add_f32_e32 v7, 1.0, v7
	v_div_scale_f32 v8, s[28:29], v7, v7, v2
	v_rcp_f32_e32 v9, v8
	v_div_scale_f32 v10, vcc, v2, v7, v2
	v_fma_f32 v11, -v8, v9, 1.0
	v_fmac_f32_e32 v9, v11, v9
	v_mul_f32_e32 v11, v10, v9
	v_fma_f32 v12, -v8, v11, v10
	v_fmac_f32_e32 v11, v12, v9
	v_fma_f32 v8, -v8, v11, v10
	v_div_fmas_f32 v8, v8, v9, v11
	v_div_fixup_f32 v2, v8, v7, v2
	ds_write_b32 v1, v2
	v_add_u32_e32 v1, 0x800, v1
	s_andn2_b64 exec, exec, s[0:1]
	s_cbranch_execnz .LBB0_22
	s_or_b64 exec, exec, s[0:1]
	s_mul_hi_i32 s0, s2, 0x2aaaaaab
	s_lshr_b32 s1, s0, 31
	s_ashr_i32 s0, s0, 4
	s_add_i32 s3, s0, s1
	s_mul_i32 s0, s3, 0x60
	s_sub_i32 s0, s2, s0
	s_lshl_b32 s4, s0, 6
	s_lshl_b32 s30, s93, 7
	s_mul_i32 s6, s3, 0x1800000
	s_ashr_i32 s5, s4, 31
	s_or_b32 s28, s30, 0x70
	s_mul_i32 s0, s93, 0x300000
	s_mul_hi_i32 s1, s3, 0x1800000
	s_mul_hi_u32 s7, s30, 0x6000
	s_add_u32 s6, s6, s0
	s_addc_u32 s7, s1, s7
	s_lshl_b64 s[0:1], s[4:5], 2
	s_add_u32 s5, s6, s0
	s_addc_u32 s7, s7, s1
	s_add_u32 s6, s60, s5
	v_lshlrev_b32_e32 v70, 2, v254
	v_mov_b32_e32 v71, 0
	s_addc_u32 s7, s61, s7
	v_lshl_add_u64 v[72:73], s[6:7], 0, v[70:71]
	s_lshl_b32 s6, s93, 9
	s_movk_i32 s29, 0x6000
	s_add_i32 s5, s30, -16
	s_add_i32 s30, s6, 0
	s_mov_b32 s31, 0xc000
	s_mov_b32 s34, 0x12000
	s_mov_b32 s35, 0x18000
	s_mov_b32 s36, 0x1e000
	s_mov_b32 s37, 0x24000
	s_mov_b32 s38, 0x2a000
	s_mov_b32 s39, 0x30000
	s_mov_b32 s40, 0x36000
	s_mov_b32 s41, 0x3c000
	s_mov_b32 s42, 0x42000
	s_mov_b32 s43, 0x48000
	s_mov_b32 s44, 0x4e000
	s_mov_b32 s45, 0x54000
	s_mov_b32 s46, 0x5a000
	s_mov_b64 s[6:7], 0x60000
	v_mov_b32_e32 v2, v71
	v_mov_b32_e32 v3, v71
	v_mov_b32_e32 v20, v71
	v_mov_b32_e32 v21, v71
	v_mov_b32_e32 v28, v71
	v_mov_b32_e32 v29, v71
	v_mov_b32_e32 v80, v71
	v_mov_b32_e32 v81, v71
	v_mov_b32_e32 v82, v71
	v_mov_b32_e32 v83, v71
	v_mov_b32_e32 v84, v71
	v_mov_b32_e32 v85, v71
	v_mov_b32_e32 v86, v71
	v_mov_b32_e32 v87, v71
	v_mov_b32_e32 v96, v71
	v_mov_b32_e32 v97, v71
	v_mov_b32_e32 v1, v71
	s_waitcnt lgkmcnt(0)
	s_barrier
	s_mov_b32 s50, 0
	s_mov_b32 s49, 0
	global_load_dword v104, v[72:73], off
	v_add_co_u32_e32 v4, vcc, s29, v72
	s_nop 1
	v_addc_co_u32_e32 v5, vcc, 0, v73, vcc
	global_load_dword v106, v[4:5], off
	v_add_co_u32_e32 v4, vcc, s31, v72
	s_nop 1
	v_addc_co_u32_e32 v5, vcc, 0, v73, vcc
	global_load_dword v108, v[4:5], off
	v_add_co_u32_e32 v4, vcc, s34, v72
	s_nop 1
	v_addc_co_u32_e32 v5, vcc, 0, v73, vcc
	global_load_dword v110, v[4:5], off
	v_add_co_u32_e32 v4, vcc, s35, v72
	s_nop 1
	v_addc_co_u32_e32 v5, vcc, 0, v73, vcc
	global_load_dword v102, v[4:5], off
	v_add_co_u32_e32 v4, vcc, s36, v72
	s_nop 1
	v_addc_co_u32_e32 v5, vcc, 0, v73, vcc
	global_load_dword v90, v[4:5], off
	v_add_co_u32_e32 v4, vcc, s37, v72
	s_nop 1
	v_addc_co_u32_e32 v5, vcc, 0, v73, vcc
	global_load_dword v92, v[4:5], off
	v_add_co_u32_e32 v4, vcc, s38, v72
	s_nop 1
	v_addc_co_u32_e32 v5, vcc, 0, v73, vcc
	global_load_dword v93, v[4:5], off
	v_add_co_u32_e32 v4, vcc, s39, v72
	s_nop 1
	v_addc_co_u32_e32 v5, vcc, 0, v73, vcc
	global_load_dword v88, v[4:5], off
	v_add_co_u32_e32 v4, vcc, s40, v72
	s_nop 1
	v_addc_co_u32_e32 v5, vcc, 0, v73, vcc
	global_load_dword v89, v[4:5], off
	v_add_co_u32_e32 v4, vcc, s41, v72
	s_nop 1
	v_addc_co_u32_e32 v5, vcc, 0, v73, vcc
	global_load_dword v94, v[4:5], off
	v_add_co_u32_e32 v4, vcc, s42, v72
	s_nop 1
	v_addc_co_u32_e32 v5, vcc, 0, v73, vcc
	global_load_dword v95, v[4:5], off
	v_add_co_u32_e32 v4, vcc, s43, v72
	s_nop 1
	v_addc_co_u32_e32 v5, vcc, 0, v73, vcc
	global_load_dword v78, v[4:5], off
	v_add_co_u32_e32 v4, vcc, s44, v72
	s_nop 1
	v_addc_co_u32_e32 v5, vcc, 0, v73, vcc
	global_load_dword v79, v[4:5], off
	v_add_co_u32_e32 v4, vcc, s45, v72
	s_nop 1
	v_addc_co_u32_e32 v5, vcc, 0, v73, vcc
	global_load_dword v74, v[4:5], off
	v_add_co_u32_e32 v4, vcc, s46, v72
	s_nop 1
	v_addc_co_u32_e32 v5, vcc, 0, v73, vcc
	global_load_dword v76, v[4:5], off
	s_add_i32 s50, s50, 1
	s_cmp_lt_u32 s50, 8
	s_cselect_b32 s48, s6, 0
	v_lshl_add_u64 v[72:73], v[72:73], 0, s[48:49]
; template <int ph> __device__ __forceinline__ void run_phase(const MArgs& a, unsigned char* lds, int tid, int lane, int wave, int G, int bx, int vcu) {
;     ...
;       for (int k0 = wave * 128; k0 < wave * 128 + 128; k0 += 16) { float wv[16];
; #pragma unroll
;         for (int q = 0; q < 16; ++q) wv[q] = W[(size_t)(k0 + q) * 6144];
; #pragma unroll
;         for (int q = 0; q < 16; ++q)
; #pragma unroll
;           for (int r = 0; r < 17; ++r) acc[r] += cond[r * 1024 + k0 + q] * wv[q]; }
.LBB0_24:
	global_load_dword v204, v[72:73], off
	v_add_co_u32_e32 v4, vcc, s29, v72
	s_nop 1
	v_addc_co_u32_e32 v5, vcc, 0, v73, vcc
	global_load_dword v206, v[4:5], off
	v_add_co_u32_e32 v4, vcc, s31, v72
	s_nop 1
	v_addc_co_u32_e32 v5, vcc, 0, v73, vcc
	global_load_dword v208, v[4:5], off
	v_add_co_u32_e32 v4, vcc, s34, v72
	s_nop 1
	v_addc_co_u32_e32 v5, vcc, 0, v73, vcc
	global_load_dword v210, v[4:5], off
	v_add_co_u32_e32 v4, vcc, s35, v72
	s_nop 1
	v_addc_co_u32_e32 v5, vcc, 0, v73, vcc
	global_load_dword v202, v[4:5], off
	v_add_co_u32_e32 v4, vcc, s36, v72
	s_nop 1
	v_addc_co_u32_e32 v5, vcc, 0, v73, vcc
	global_load_dword v190, v[4:5], off
	v_add_co_u32_e32 v4, vcc, s37, v72
	s_nop 1
	v_addc_co_u32_e32 v5, vcc, 0, v73, vcc
	global_load_dword v192, v[4:5], off
	v_add_co_u32_e32 v4, vcc, s38, v72
	s_nop 1
	v_addc_co_u32_e32 v5, vcc, 0, v73, vcc
	global_load_dword v193, v[4:5], off
	v_add_co_u32_e32 v4, vcc, s39, v72
	s_nop 1
	v_addc_co_u32_e32 v5, vcc, 0, v73, vcc
	global_load_dword v188, v[4:5], off
	v_add_co_u32_e32 v4, vcc, s40, v72
	s_nop 1
	v_addc_co_u32_e32 v5, vcc, 0, v73, vcc
	global_load_dword v189, v[4:5], off
	v_add_co_u32_e32 v4, vcc, s41, v72
	s_nop 1
	v_addc_co_u32_e32 v5, vcc, 0, v73, vcc
	global_load_dword v194, v[4:5], off
	v_add_co_u32_e32 v4, vcc, s42, v72
	s_nop 1
	v_addc_co_u32_e32 v5, vcc, 0, v73, vcc
	global_load_dword v195, v[4:5], off
	v_add_co_u32_e32 v4, vcc, s43, v72
	s_nop 1
	v_addc_co_u32_e32 v5, vcc, 0, v73, vcc
	global_load_dword v178, v[4:5], off
	v_add_co_u32_e32 v4, vcc, s44, v72
	s_nop 1
	v_addc_co_u32_e32 v5, vcc, 0, v73, vcc
	global_load_dword v179, v[4:5], off
	v_add_co_u32_e32 v4, vcc, s45, v72
	s_nop 1
	v_addc_co_u32_e32 v5, vcc, 0, v73, vcc
	global_load_dword v174, v[4:5], off
	v_add_co_u32_e32 v4, vcc, s46, v72
	s_nop 1
	v_addc_co_u32_e32 v5, vcc, 0, v73, vcc
	global_load_dword v176, v[4:5], off
	s_add_i32 s50, s50, 1
	s_cmp_lt_u32 s50, 8
	s_cselect_b32 s48, s6, 0
	v_lshl_add_u64 v[72:73], v[72:73], 0, s[48:49]
	s_add_i32 s47, s30, 0x10000
	v_mov_b32_e32 v69, s30
	s_add_i32 s5, s5, 16
	v_mov_b32_e32 v4, s47
	ds_read_b128 v[4:7], v4
	s_add_i32 s47, s30, 0x10010
	s_waitcnt vmcnt(31) lgkmcnt(0)
	v_fmac_f32_e32 v1, v104, v4
	s_waitcnt vmcnt(30)
	v_fmac_f32_e32 v1, v106, v5
	s_waitcnt vmcnt(29)
	v_fmac_f32_e32 v1, v108, v6
	s_waitcnt vmcnt(28)
	v_fmac_f32_e32 v1, v110, v7
	ds_read_b128 v[4:7], v69
	ds_read_b128 v[112:115], v69 offset:16
	ds_read_b128 v[64:67], v69 offset:32
	ds_read_b128 v[52:55], v69 offset:48
	ds_read_b128 v[116:119], v69 offset:4112
	ds_read_b128 v[8:11], v69 offset:4096
	s_waitcnt lgkmcnt(5)
	v_mov_b32_e32 v12, v4
	v_mov_b32_e32 v4, v6
	s_waitcnt lgkmcnt(0)
	v_mov_b32_e32 v13, v8
	v_pk_fma_f32 v[2:3], v[104:105], v[12:13], v[2:3] op_sel_hi:[0,1,1]
	v_mov_b32_e32 v8, v5
	v_pk_fma_f32 v[2:3], v[106:107], v[8:9], v[2:3] op_sel_hi:[0,1,1]
	v_mov_b32_e32 v5, v10
	v_pk_fma_f32 v[2:3], v[108:109], v[4:5], v[2:3] op_sel_hi:[0,1,1]
	v_mov_b32_e32 v10, v7
	v_pk_fma_f32 v[2:3], v[110:111], v[10:11], v[2:3] op_sel_hi:[0,1,1]
	v_mov_b32_e32 v4, v112
	v_mov_b32_e32 v5, v116
	s_waitcnt vmcnt(27)
	v_pk_fma_f32 v[128:129], v[102:103], v[4:5], v[2:3] op_sel_hi:[0,1,1]
	ds_read_b128 v[56:59], v69 offset:8208
	ds_read_b128 v[60:63], v69 offset:12304
	ds_read_b128 v[2:5], v69 offset:8192
	ds_read_b128 v[6:9], v69 offset:12288
	v_mov_b32_e32 v116, v113
	s_waitcnt lgkmcnt(1)
	v_mov_b32_e32 v10, v2
	s_waitcnt lgkmcnt(0)
	v_mov_b32_e32 v11, v6
	v_pk_fma_f32 v[10:11], v[104:105], v[10:11], v[20:21] op_sel_hi:[0,1,1]
	v_mov_b32_e32 v6, v3
	v_pk_fma_f32 v[2:3], v[106:107], v[6:7], v[10:11] op_sel_hi:[0,1,1]
	v_mov_b32_e32 v6, v4
	v_mov_b32_e32 v7, v8
	v_pk_fma_f32 v[2:3], v[108:109], v[6:7], v[2:3] op_sel_hi:[0,1,1]
	v_mov_b32_e32 v8, v5
	v_pk_fma_f32 v[2:3], v[110:111], v[8:9], v[2:3] op_sel_hi:[0,1,1]
	v_mov_b32_e32 v4, v56
	v_mov_b32_e32 v5, v60
	v_pk_fma_f32 v[100:101], v[102:103], v[4:5], v[2:3] op_sel_hi:[0,1,1]
	ds_read_b128 v[44:47], v69 offset:16400
	ds_read_b128 v[48:51], v69 offset:20496
	ds_read_b128 v[2:5], v69 offset:16384
	ds_read_b128 v[6:9], v69 offset:20480
	v_mov_b32_e32 v60, v57
	s_waitcnt lgkmcnt(1)
	v_mov_b32_e32 v10, v2
	s_waitcnt lgkmcnt(0)
	v_mov_b32_e32 v11, v6
	v_pk_fma_f32 v[10:11], v[104:105], v[10:11], v[28:29] op_sel_hi:[0,1,1]
	v_mov_b32_e32 v6, v3
	v_pk_fma_f32 v[2:3], v[106:107], v[6:7], v[10:11] op_sel_hi:[0,1,1]
	v_mov_b32_e32 v6, v4
	v_mov_b32_e32 v7, v8
	v_pk_fma_f32 v[2:3], v[108:109], v[6:7], v[2:3] op_sel_hi:[0,1,1]
	v_mov_b32_e32 v8, v5
	v_pk_fma_f32 v[2:3], v[110:111], v[8:9], v[2:3] op_sel_hi:[0,1,1]
	v_mov_b32_e32 v4, v44
	v_mov_b32_e32 v5, v48
	v_pk_fma_f32 v[98:99], v[102:103], v[4:5], v[2:3] op_sel_hi:[0,1,1]
	ds_read_b128 v[36:39], v69 offset:24592
	ds_read_b128 v[40:43], v69 offset:28688
	ds_read_b128 v[2:5], v69 offset:24576
	ds_read_b128 v[6:9], v69 offset:28672
	s_waitcnt vmcnt(22)
	v_mov_b32_e32 v44, v89
	s_waitcnt vmcnt(20)
	v_mov_b32_e32 v56, v95
	v_mov_b32_e32 v48, v45
	s_waitcnt lgkmcnt(1)
	v_mov_b32_e32 v10, v2
	s_waitcnt lgkmcnt(0)
	v_mov_b32_e32 v11, v6
	v_pk_fma_f32 v[10:11], v[104:105], v[10:11], v[80:81] op_sel_hi:[0,1,1]
	v_mov_b32_e32 v6, v3
	v_pk_fma_f32 v[2:3], v[106:107], v[6:7], v[10:11] op_sel_hi:[0,1,1]
	v_mov_b32_e32 v6, v4
	v_mov_b32_e32 v7, v8
	v_pk_fma_f32 v[2:3], v[108:109], v[6:7], v[2:3] op_sel_hi:[0,1,1]
	v_mov_b32_e32 v8, v5
	v_pk_fma_f32 v[2:3], v[110:111], v[8:9], v[2:3] op_sel_hi:[0,1,1]
	v_mov_b32_e32 v4, v36
	v_mov_b32_e32 v5, v40
	v_pk_fma_f32 v[80:81], v[102:103], v[4:5], v[2:3] op_sel_hi:[0,1,1]
	ds_read_b128 v[28:31], v69 offset:32784
	ds_read_b128 v[32:35], v69 offset:36880
	ds_read_b128 v[2:5], v69 offset:32768
	ds_read_b128 v[6:9], v69 offset:36864
	s_waitcnt vmcnt(18)
; template <int ph> __device__ __forceinline__ void run_phase(const MArgs& a, unsigned char* lds, int tid, int lane, int wave, int G, int bx, int vcu) {
;     ...
;       for (int k0 = wave * 128; k0 < wave * 128 + 128; k0 += 16) { float wv[16];
; #pragma unroll
;         for (int q = 0; q < 16; ++q) wv[q] = W[(size_t)(k0 + q) * 6144];
; #pragma unroll
;         for (int q = 0; q < 16; ++q)
; #pragma unroll
;           for (int r = 0; r < 17; ++r) acc[r] += cond[r * 1024 + k0 + q] * wv[q]; }
	v_mov_b32_e32 v36, v79
	v_mov_b32_e32 v40, v37
	v_pk_fma_f32 v[40:41], v[90:91], v[40:41], v[80:81] op_sel_hi:[0,1,1]
	s_waitcnt lgkmcnt(1)
	v_mov_b32_e32 v10, v2
	s_waitcnt lgkmcnt(0)
	v_mov_b32_e32 v11, v6
	v_pk_fma_f32 v[10:11], v[104:105], v[10:11], v[82:83] op_sel_hi:[0,1,1]
	v_mov_b32_e32 v6, v3
	v_pk_fma_f32 v[2:3], v[106:107], v[6:7], v[10:11] op_sel_hi:[0,1,1]
	v_mov_b32_e32 v6, v4
	v_mov_b32_e32 v7, v8
	v_pk_fma_f32 v[2:3], v[108:109], v[6:7], v[2:3] op_sel_hi:[0,1,1]
	v_mov_b32_e32 v8, v5
	v_pk_fma_f32 v[2:3], v[110:111], v[8:9], v[2:3] op_sel_hi:[0,1,1]
	v_mov_b32_e32 v4, v28
	v_mov_b32_e32 v5, v32
	v_pk_fma_f32 v[82:83], v[102:103], v[4:5], v[2:3] op_sel_hi:[0,1,1]
	ds_read_b128 v[20:23], v69 offset:40976
	ds_read_b128 v[24:27], v69 offset:45072
	ds_read_b128 v[2:5], v69 offset:40960
	ds_read_b128 v[6:9], v69 offset:45056
	v_mov_b32_e32 v32, v29
	v_mov_b32_e32 v28, v58
	v_mov_b32_e32 v29, v62
	s_waitcnt lgkmcnt(1)
	v_mov_b32_e32 v10, v2
	s_waitcnt lgkmcnt(0)
	v_mov_b32_e32 v11, v6
	v_pk_fma_f32 v[10:11], v[104:105], v[10:11], v[84:85] op_sel_hi:[0,1,1]
	v_mov_b32_e32 v6, v3
	v_pk_fma_f32 v[2:3], v[106:107], v[6:7], v[10:11] op_sel_hi:[0,1,1]
	v_mov_b32_e32 v6, v4
	v_mov_b32_e32 v7, v8
	v_pk_fma_f32 v[2:3], v[108:109], v[6:7], v[2:3] op_sel_hi:[0,1,1]
	v_mov_b32_e32 v8, v5
	v_pk_fma_f32 v[2:3], v[110:111], v[8:9], v[2:3] op_sel_hi:[0,1,1]
	v_mov_b32_e32 v4, v20
	v_mov_b32_e32 v5, v24
	v_pk_fma_f32 v[84:85], v[102:103], v[4:5], v[2:3] op_sel_hi:[0,1,1]
	ds_read_b128 v[12:15], v69 offset:49168
	ds_read_b128 v[16:19], v69 offset:53264
	ds_read_b128 v[2:5], v69 offset:49152
	ds_read_b128 v[6:9], v69 offset:53248
	v_mov_b32_e32 v24, v21
	v_mov_b32_e32 v20, v64
	v_mov_b32_e32 v62, v59
	s_waitcnt lgkmcnt(1)
	v_mov_b32_e32 v10, v2
	s_waitcnt lgkmcnt(0)
	v_mov_b32_e32 v11, v6
	v_pk_fma_f32 v[10:11], v[104:105], v[10:11], v[86:87] op_sel_hi:[0,1,1]
	v_mov_b32_e32 v6, v3
	v_pk_fma_f32 v[2:3], v[106:107], v[6:7], v[10:11] op_sel_hi:[0,1,1]
	v_mov_b32_e32 v6, v4
	v_mov_b32_e32 v7, v8
	v_pk_fma_f32 v[2:3], v[108:109], v[6:7], v[2:3] op_sel_hi:[0,1,1]
	v_mov_b32_e32 v8, v5
	v_pk_fma_f32 v[2:3], v[110:111], v[8:9], v[2:3] op_sel_hi:[0,1,1]
	v_mov_b32_e32 v4, v12
	v_mov_b32_e32 v5, v16
	v_pk_fma_f32 v[86:87], v[102:103], v[4:5], v[2:3] op_sel_hi:[0,1,1]
	ds_read_b128 v[4:7], v69 offset:57360
	ds_read_b128 v[8:11], v69 offset:61456
	ds_read_b128 v[120:123], v69 offset:57344
	ds_read_b128 v[124:127], v69 offset:61440
	v_mov_b32_e32 v16, v13
	v_mov_b32_e32 v12, v114
	v_mov_b32_e32 v13, v118
	s_waitcnt lgkmcnt(1)
	v_mov_b32_e32 v2, v120
	s_waitcnt lgkmcnt(0)
	v_mov_b32_e32 v3, v124
	v_pk_fma_f32 v[2:3], v[104:105], v[2:3], v[96:97] op_sel_hi:[0,1,1]
	v_mov_b32_e32 v124, v121
	v_pk_fma_f32 v[2:3], v[106:107], v[124:125], v[2:3] op_sel_hi:[0,1,1]
	v_mov_b32_e32 v96, v122
	v_mov_b32_e32 v97, v126
	v_pk_fma_f32 v[2:3], v[108:109], v[96:97], v[2:3] op_sel_hi:[0,1,1]
	v_mov_b32_e32 v126, v123
	v_pk_fma_f32 v[2:3], v[110:111], v[126:127], v[2:3] op_sel_hi:[0,1,1]
	v_mov_b32_e32 v96, v4
	v_mov_b32_e32 v97, v8
	v_pk_fma_f32 v[96:97], v[102:103], v[96:97], v[2:3] op_sel_hi:[0,1,1]
	v_mov_b32_e32 v2, s47
	v_mov_b32_e32 v8, v5
	ds_read_b128 v[2:5], v2
	v_mov_b32_e32 v103, v90
	s_add_i32 s47, s30, 0x10020
	v_mov_b32_e32 v118, v115
	v_pk_fma_f32 v[32:33], v[90:91], v[32:33], v[82:83] op_sel_hi:[0,1,1]
	s_waitcnt lgkmcnt(0)
	v_pk_mul_f32 v[2:3], v[102:103], v[2:3]
	ds_read_b128 v[102:105], v69 offset:4128
	v_add_f32_e32 v1, v1, v2
	v_add_f32_e32 v1, v1, v3
	v_pk_mul_f32 v[2:3], v[92:93], v[4:5]
	v_pk_fma_f32 v[24:25], v[90:91], v[24:25], v[84:85] op_sel_hi:[0,1,1]
	v_add_f32_e32 v1, v1, v2
	v_mov_b32_e32 v2, s47
	v_add_f32_e32 v1, v1, v3
	ds_read_b128 v[2:5], v2
	s_add_i32 s47, s30, 0x10030
	s_waitcnt lgkmcnt(1)
	v_mov_b32_e32 v21, v102
	v_mov_b32_e32 v102, v65
	v_pk_fma_f32 v[16:17], v[90:91], v[16:17], v[86:87] op_sel_hi:[0,1,1]
	s_waitcnt lgkmcnt(0)
	v_pk_mul_f32 v[2:3], v[88:89], v[2:3]
	v_pk_fma_f32 v[8:9], v[90:91], v[8:9], v[96:97] op_sel_hi:[0,1,1]
	v_add_f32_e32 v1, v1, v2
	v_add_f32_e32 v1, v1, v3
	v_pk_mul_f32 v[2:3], v[94:95], v[4:5]
	s_add_i32 s30, s30, 64
	v_add_f32_e32 v1, v1, v2
	v_mov_b32_e32 v2, s47
	v_add_f32_e32 v1, v1, v3
	ds_read_b128 v[2:5], v2
	s_cmp_ge_u32 s5, s28
	s_waitcnt lgkmcnt(0)
	v_pk_mul_f32 v[2:3], v[78:79], v[2:3]
	s_nop 0
	v_add_f32_e32 v1, v1, v2
	v_add_f32_e32 v1, v1, v3
	v_pk_fma_f32 v[2:3], v[90:91], v[116:117], v[128:129] op_sel_hi:[0,1,1]
	v_pk_fma_f32 v[2:3], v[92:93], v[12:13], v[2:3] op_sel_hi:[0,1,1]
	v_mov_b32_e32 v12, v93
	v_pk_fma_f32 v[2:3], v[12:13], v[118:119], v[2:3] op_sel_hi:[0,1,1]
	v_pk_fma_f32 v[2:3], v[88:89], v[20:21], v[2:3] op_sel_hi:[0,1,1]
	v_mov_b32_e32 v20, v66
	v_mov_b32_e32 v21, v104
	v_mov_b32_e32 v104, v67
	ds_read_b128 v[64:67], v69 offset:4144
	v_pk_fma_f32 v[2:3], v[44:45], v[102:103], v[2:3] op_sel_hi:[0,1,1]
	v_pk_fma_f32 v[2:3], v[94:95], v[20:21], v[2:3] op_sel_hi:[0,1,1]
	v_pk_fma_f32 v[2:3], v[56:57], v[104:105], v[2:3] op_sel_hi:[0,1,1]
	v_mov_b32_e32 v20, v52
	s_waitcnt lgkmcnt(0)
	v_mov_b32_e32 v21, v64
	v_pk_fma_f32 v[2:3], v[78:79], v[20:21], v[2:3] op_sel_hi:[0,1,1]
	v_mov_b32_e32 v64, v53
	v_pk_fma_f32 v[2:3], v[36:37], v[64:65], v[2:3] op_sel_hi:[0,1,1]
	v_mov_b32_e32 v20, v54
	v_mov_b32_e32 v21, v66
	s_waitcnt vmcnt(17)
	v_pk_fma_f32 v[2:3], v[74:75], v[20:21], v[2:3] op_sel_hi:[0,1,1]
	v_mov_b32_e32 v66, v55
	v_pk_fma_f32 v[20:21], v[90:91], v[60:61], v[100:101] op_sel_hi:[0,1,1]
	ds_read_b128 v[52:55], v69 offset:8224
	ds_read_b128 v[58:61], v69 offset:12320
	v_pk_fma_f32 v[20:21], v[92:93], v[28:29], v[20:21] op_sel_hi:[0,1,1]
	v_pk_fma_f32 v[20:21], v[12:13], v[62:63], v[20:21] op_sel_hi:[0,1,1]
	s_waitcnt vmcnt(16)
; template <int ph> __device__ __forceinline__ void run_phase(const MArgs& a, unsigned char* lds, int tid, int lane, int wave, int G, int bx, int vcu) {
;     ...
;         for (int q = 0; q < 16; ++q)
; #pragma unroll
;           for (int r = 0; r < 17; ++r) acc[r] += cond[r * 1024 + k0 + q] * wv[q]; }
	v_pk_fma_f32 v[2:3], v[76:77], v[66:67], v[2:3] op_sel_hi:[0,1,1]
	s_waitcnt lgkmcnt(1)
	v_mov_b32_e32 v28, v52
	s_waitcnt lgkmcnt(0)
	v_mov_b32_e32 v29, v58
	v_pk_fma_f32 v[20:21], v[88:89], v[28:29], v[20:21] op_sel_hi:[0,1,1]
	v_mov_b32_e32 v58, v53
	v_pk_fma_f32 v[20:21], v[44:45], v[58:59], v[20:21] op_sel_hi:[0,1,1]
	v_mov_b32_e32 v28, v54
	v_mov_b32_e32 v29, v60
	v_pk_fma_f32 v[20:21], v[94:95], v[28:29], v[20:21] op_sel_hi:[0,1,1]
	v_mov_b32_e32 v60, v55
	v_pk_fma_f32 v[20:21], v[56:57], v[60:61], v[20:21] op_sel_hi:[0,1,1]
	ds_read_b128 v[52:55], v69 offset:8240
	ds_read_b128 v[58:61], v69 offset:12336
	s_waitcnt lgkmcnt(1)
	v_mov_b32_e32 v28, v52
	s_waitcnt lgkmcnt(0)
	v_mov_b32_e32 v29, v58
	v_pk_fma_f32 v[20:21], v[78:79], v[28:29], v[20:21] op_sel_hi:[0,1,1]
	v_mov_b32_e32 v58, v53
	v_pk_fma_f32 v[20:21], v[36:37], v[58:59], v[20:21] op_sel_hi:[0,1,1]
	v_mov_b32_e32 v28, v54
	v_mov_b32_e32 v29, v60
	v_pk_fma_f32 v[20:21], v[74:75], v[28:29], v[20:21] op_sel_hi:[0,1,1]
	v_pk_fma_f32 v[28:29], v[90:91], v[48:49], v[98:99] op_sel_hi:[0,1,1]
	v_mov_b32_e32 v48, v46
	v_mov_b32_e32 v49, v50
	v_pk_fma_f32 v[28:29], v[92:93], v[48:49], v[28:29] op_sel_hi:[0,1,1]
	v_mov_b32_e32 v50, v47
	v_pk_fma_f32 v[28:29], v[12:13], v[50:51], v[28:29] op_sel_hi:[0,1,1]
	ds_read_b128 v[46:49], v69 offset:16416
	ds_read_b128 v[50:53], v69 offset:20512
	v_mov_b32_e32 v60, v55
	v_pk_fma_f32 v[20:21], v[76:77], v[60:61], v[20:21] op_sel_hi:[0,1,1]
	s_waitcnt lgkmcnt(1)
	v_mov_b32_e32 v54, v46
	s_waitcnt lgkmcnt(0)
	v_mov_b32_e32 v55, v50
	v_pk_fma_f32 v[28:29], v[88:89], v[54:55], v[28:29] op_sel_hi:[0,1,1]
	v_mov_b32_e32 v50, v47
	v_pk_fma_f32 v[28:29], v[44:45], v[50:51], v[28:29] op_sel_hi:[0,1,1]
	v_mov_b32_e32 v46, v48
	v_mov_b32_e32 v47, v52
	v_pk_fma_f32 v[28:29], v[94:95], v[46:47], v[28:29] op_sel_hi:[0,1,1]
	v_mov_b32_e32 v52, v49
	v_pk_fma_f32 v[28:29], v[56:57], v[52:53], v[28:29] op_sel_hi:[0,1,1]
	ds_read_b128 v[46:49], v69 offset:16432
	ds_read_b128 v[50:53], v69 offset:20528
	s_waitcnt lgkmcnt(1)
	v_mov_b32_e32 v54, v46
	s_waitcnt lgkmcnt(0)
	v_mov_b32_e32 v55, v50
	v_pk_fma_f32 v[28:29], v[78:79], v[54:55], v[28:29] op_sel_hi:[0,1,1]
	v_mov_b32_e32 v50, v47
	v_pk_fma_f32 v[28:29], v[36:37], v[50:51], v[28:29] op_sel_hi:[0,1,1]
	v_mov_b32_e32 v46, v48
	v_mov_b32_e32 v47, v52
	v_pk_fma_f32 v[28:29], v[74:75], v[46:47], v[28:29] op_sel_hi:[0,1,1]
	v_mov_b32_e32 v46, v38
	v_mov_b32_e32 v47, v42
	v_pk_fma_f32 v[40:41], v[92:93], v[46:47], v[40:41] op_sel_hi:[0,1,1]
	v_mov_b32_e32 v42, v39
	v_mov_b32_e32 v52, v49
	v_pk_fma_f32 v[42:43], v[12:13], v[42:43], v[40:41] op_sel_hi:[0,1,1]
	ds_read_b128 v[38:41], v69 offset:24608
	ds_read_b128 v[46:49], v69 offset:28704
	v_pk_fma_f32 v[28:29], v[76:77], v[52:53], v[28:29] op_sel_hi:[0,1,1]
	s_waitcnt lgkmcnt(1)
	v_mov_b32_e32 v50, v38
	s_waitcnt lgkmcnt(0)
	v_mov_b32_e32 v51, v46
	v_pk_fma_f32 v[42:43], v[88:89], v[50:51], v[42:43] op_sel_hi:[0,1,1]
	v_mov_b32_e32 v46, v39
	v_pk_fma_f32 v[38:39], v[44:45], v[46:47], v[42:43] op_sel_hi:[0,1,1]
	v_mov_b32_e32 v42, v40
	v_mov_b32_e32 v43, v48
	v_pk_fma_f32 v[38:39], v[94:95], v[42:43], v[38:39] op_sel_hi:[0,1,1]
	v_mov_b32_e32 v48, v41
	v_pk_fma_f32 v[42:43], v[56:57], v[48:49], v[38:39] op_sel_hi:[0,1,1]
	ds_read_b128 v[38:41], v69 offset:24624
	ds_read_b128 v[46:49], v69 offset:28720
	s_waitcnt lgkmcnt(1)
	v_mov_b32_e32 v50, v38
	s_waitcnt lgkmcnt(0)
	v_mov_b32_e32 v51, v46
	v_pk_fma_f32 v[42:43], v[78:79], v[50:51], v[42:43] op_sel_hi:[0,1,1]
	v_mov_b32_e32 v46, v39
	v_pk_fma_f32 v[38:39], v[36:37], v[46:47], v[42:43] op_sel_hi:[0,1,1]
	v_mov_b32_e32 v42, v40
	v_mov_b32_e32 v43, v48
	v_pk_fma_f32 v[38:39], v[74:75], v[42:43], v[38:39] op_sel_hi:[0,1,1]
	v_mov_b32_e32 v48, v41
	v_pk_fma_f32 v[80:81], v[76:77], v[48:49], v[38:39] op_sel_hi:[0,1,1]
	v_mov_b32_e32 v38, v30
	v_mov_b32_e32 v39, v34
	v_pk_fma_f32 v[32:33], v[92:93], v[38:39], v[32:33] op_sel_hi:[0,1,1]
	v_mov_b32_e32 v34, v31
	v_pk_fma_f32 v[34:35], v[12:13], v[34:35], v[32:33] op_sel_hi:[0,1,1]
	ds_read_b128 v[30:33], v69 offset:32800
	ds_read_b128 v[38:41], v69 offset:36896
	s_waitcnt lgkmcnt(1)
	v_mov_b32_e32 v42, v30
	s_waitcnt lgkmcnt(0)
	v_mov_b32_e32 v43, v38
	v_pk_fma_f32 v[34:35], v[88:89], v[42:43], v[34:35] op_sel_hi:[0,1,1]
	v_mov_b32_e32 v38, v31
	v_pk_fma_f32 v[30:31], v[44:45], v[38:39], v[34:35] op_sel_hi:[0,1,1]
	v_mov_b32_e32 v34, v32
	v_mov_b32_e32 v35, v40
	v_pk_fma_f32 v[30:31], v[94:95], v[34:35], v[30:31] op_sel_hi:[0,1,1]
	v_mov_b32_e32 v40, v33
	v_pk_fma_f32 v[34:35], v[56:57], v[40:41], v[30:31] op_sel_hi:[0,1,1]
	ds_read_b128 v[30:33], v69 offset:32816
	ds_read_b128 v[38:41], v69 offset:36912
	s_waitcnt lgkmcnt(1)
	v_mov_b32_e32 v42, v30
	s_waitcnt lgkmcnt(0)
	v_mov_b32_e32 v43, v38
	v_pk_fma_f32 v[34:35], v[78:79], v[42:43], v[34:35] op_sel_hi:[0,1,1]
	v_mov_b32_e32 v38, v31
	v_pk_fma_f32 v[30:31], v[36:37], v[38:39], v[34:35] op_sel_hi:[0,1,1]
	v_mov_b32_e32 v34, v32
	v_mov_b32_e32 v35, v40
	v_pk_fma_f32 v[30:31], v[74:75], v[34:35], v[30:31] op_sel_hi:[0,1,1]
	v_mov_b32_e32 v40, v33
	v_pk_fma_f32 v[82:83], v[76:77], v[40:41], v[30:31] op_sel_hi:[0,1,1]
	v_mov_b32_e32 v30, v22
	v_mov_b32_e32 v31, v26
	v_pk_fma_f32 v[24:25], v[92:93], v[30:31], v[24:25] op_sel_hi:[0,1,1]
	v_mov_b32_e32 v26, v23
	v_pk_fma_f32 v[26:27], v[12:13], v[26:27], v[24:25] op_sel_hi:[0,1,1]
	ds_read_b128 v[22:25], v69 offset:40992
	ds_read_b128 v[30:33], v69 offset:45088
	s_waitcnt lgkmcnt(1)
	v_mov_b32_e32 v34, v22
	s_waitcnt lgkmcnt(0)
; template <int ph> __device__ __forceinline__ void run_phase(const MArgs& a, unsigned char* lds, int tid, int lane, int wave, int G, int bx, int vcu) {
;     ...
;       for (int k0 = wave * 128; k0 < wave * 128 + 128; k0 += 16) { float wv[16];
; #pragma unroll
;         for (int q = 0; q < 16; ++q) wv[q] = W[(size_t)(k0 + q) * 6144];
; #pragma unroll
;         for (int q = 0; q < 16; ++q)
; #pragma unroll
;           for (int r = 0; r < 17; ++r) acc[r] += cond[r * 1024 + k0 + q] * wv[q]; }
	v_mov_b32_e32 v35, v30
	v_pk_fma_f32 v[26:27], v[88:89], v[34:35], v[26:27] op_sel_hi:[0,1,1]
	v_mov_b32_e32 v30, v23
	v_pk_fma_f32 v[22:23], v[44:45], v[30:31], v[26:27] op_sel_hi:[0,1,1]
	v_mov_b32_e32 v26, v24
	v_mov_b32_e32 v27, v32
	v_pk_fma_f32 v[22:23], v[94:95], v[26:27], v[22:23] op_sel_hi:[0,1,1]
	v_mov_b32_e32 v32, v25
	v_pk_fma_f32 v[26:27], v[56:57], v[32:33], v[22:23] op_sel_hi:[0,1,1]
	ds_read_b128 v[22:25], v69 offset:41008
	ds_read_b128 v[30:33], v69 offset:45104
	s_waitcnt lgkmcnt(1)
	v_mov_b32_e32 v34, v22
	s_waitcnt lgkmcnt(0)
	v_mov_b32_e32 v35, v30
	v_pk_fma_f32 v[26:27], v[78:79], v[34:35], v[26:27] op_sel_hi:[0,1,1]
	v_mov_b32_e32 v30, v23
	v_pk_fma_f32 v[22:23], v[36:37], v[30:31], v[26:27] op_sel_hi:[0,1,1]
	v_mov_b32_e32 v26, v24
	v_mov_b32_e32 v27, v32
	v_pk_fma_f32 v[22:23], v[74:75], v[26:27], v[22:23] op_sel_hi:[0,1,1]
	v_mov_b32_e32 v32, v25
	v_pk_fma_f32 v[84:85], v[76:77], v[32:33], v[22:23] op_sel_hi:[0,1,1]
	v_mov_b32_e32 v22, v14
	v_mov_b32_e32 v23, v18
	v_pk_fma_f32 v[16:17], v[92:93], v[22:23], v[16:17] op_sel_hi:[0,1,1]
	v_mov_b32_e32 v18, v15
	v_pk_fma_f32 v[18:19], v[12:13], v[18:19], v[16:17] op_sel_hi:[0,1,1]
	ds_read_b128 v[14:17], v69 offset:49184
	ds_read_b128 v[22:25], v69 offset:53280
	s_waitcnt lgkmcnt(1)
	v_mov_b32_e32 v26, v14
	s_waitcnt lgkmcnt(0)
	v_mov_b32_e32 v27, v22
	v_pk_fma_f32 v[18:19], v[88:89], v[26:27], v[18:19] op_sel_hi:[0,1,1]
	v_mov_b32_e32 v22, v15
	v_pk_fma_f32 v[14:15], v[44:45], v[22:23], v[18:19] op_sel_hi:[0,1,1]
	v_mov_b32_e32 v18, v16
	v_mov_b32_e32 v19, v24
	v_pk_fma_f32 v[14:15], v[94:95], v[18:19], v[14:15] op_sel_hi:[0,1,1]
	v_mov_b32_e32 v24, v17
	v_pk_fma_f32 v[18:19], v[56:57], v[24:25], v[14:15] op_sel_hi:[0,1,1]
	ds_read_b128 v[14:17], v69 offset:49200
	ds_read_b128 v[22:25], v69 offset:53296
	s_waitcnt lgkmcnt(1)
	v_mov_b32_e32 v26, v14
	s_waitcnt lgkmcnt(0)
	v_mov_b32_e32 v27, v22
	v_pk_fma_f32 v[18:19], v[78:79], v[26:27], v[18:19] op_sel_hi:[0,1,1]
	v_mov_b32_e32 v22, v15
	v_pk_fma_f32 v[14:15], v[36:37], v[22:23], v[18:19] op_sel_hi:[0,1,1]
	v_mov_b32_e32 v18, v16
	v_mov_b32_e32 v19, v24
	v_pk_fma_f32 v[14:15], v[74:75], v[18:19], v[14:15] op_sel_hi:[0,1,1]
	v_mov_b32_e32 v24, v17
	v_pk_fma_f32 v[86:87], v[76:77], v[24:25], v[14:15] op_sel_hi:[0,1,1]
	v_mov_b32_e32 v14, v6
	v_mov_b32_e32 v15, v10
	v_pk_fma_f32 v[8:9], v[92:93], v[14:15], v[8:9] op_sel_hi:[0,1,1]
	v_mov_b32_e32 v10, v7
	v_pk_fma_f32 v[14:15], v[12:13], v[10:11], v[8:9] op_sel_hi:[0,1,1]
	ds_read_b128 v[6:9], v69 offset:57376
	ds_read_b128 v[10:13], v69 offset:61472
	s_waitcnt lgkmcnt(1)
	v_mov_b32_e32 v16, v6
	s_waitcnt lgkmcnt(0)
	v_mov_b32_e32 v17, v10
	v_pk_fma_f32 v[14:15], v[88:89], v[16:17], v[14:15] op_sel_hi:[0,1,1]
	v_mov_b32_e32 v10, v7
	v_pk_fma_f32 v[6:7], v[44:45], v[10:11], v[14:15] op_sel_hi:[0,1,1]
	v_mov_b32_e32 v10, v8
	v_mov_b32_e32 v11, v12
	v_pk_fma_f32 v[6:7], v[94:95], v[10:11], v[6:7] op_sel_hi:[0,1,1]
	v_mov_b32_e32 v12, v9
	v_pk_fma_f32 v[14:15], v[56:57], v[12:13], v[6:7] op_sel_hi:[0,1,1]
	ds_read_b128 v[6:9], v69 offset:57392
	ds_read_b128 v[10:13], v69 offset:61488
	s_waitcnt lgkmcnt(1)
	v_mov_b32_e32 v16, v6
	s_waitcnt lgkmcnt(0)
	v_mov_b32_e32 v17, v10
	v_pk_fma_f32 v[14:15], v[78:79], v[16:17], v[14:15] op_sel_hi:[0,1,1]
	v_mov_b32_e32 v10, v7
	v_pk_fma_f32 v[6:7], v[36:37], v[10:11], v[14:15] op_sel_hi:[0,1,1]
	v_mov_b32_e32 v10, v8
	v_mov_b32_e32 v11, v12
	v_pk_fma_f32 v[6:7], v[74:75], v[10:11], v[6:7] op_sel_hi:[0,1,1]
	v_mov_b32_e32 v75, v76
	v_pk_mul_f32 v[4:5], v[74:75], v[4:5]
	v_mov_b32_e32 v12, v9
	v_add_f32_e32 v1, v1, v4
	v_pk_fma_f32 v[96:97], v[76:77], v[12:13], v[6:7] op_sel_hi:[0,1,1]
	v_add_f32_e32 v1, v1, v5
	s_cmp_lt_u32 s50, 8
	s_cbranch_scc0 .Lmods_dummy
	global_load_dword v104, v[72:73], off
	v_add_co_u32_e32 v4, vcc, s29, v72
	s_nop 1
	v_addc_co_u32_e32 v5, vcc, 0, v73, vcc
	global_load_dword v106, v[4:5], off
	v_add_co_u32_e32 v4, vcc, s31, v72
	s_nop 1
	v_addc_co_u32_e32 v5, vcc, 0, v73, vcc
	global_load_dword v108, v[4:5], off
	v_add_co_u32_e32 v4, vcc, s34, v72
	s_nop 1
	v_addc_co_u32_e32 v5, vcc, 0, v73, vcc
	global_load_dword v110, v[4:5], off
	v_add_co_u32_e32 v4, vcc, s35, v72
	s_nop 1
	v_addc_co_u32_e32 v5, vcc, 0, v73, vcc
	global_load_dword v102, v[4:5], off
	v_add_co_u32_e32 v4, vcc, s36, v72
	s_nop 1
	v_addc_co_u32_e32 v5, vcc, 0, v73, vcc
	global_load_dword v90, v[4:5], off
	v_add_co_u32_e32 v4, vcc, s37, v72
	s_nop 1
	v_addc_co_u32_e32 v5, vcc, 0, v73, vcc
	global_load_dword v92, v[4:5], off
	v_add_co_u32_e32 v4, vcc, s38, v72
	s_nop 1
	v_addc_co_u32_e32 v5, vcc, 0, v73, vcc
	global_load_dword v93, v[4:5], off
	v_add_co_u32_e32 v4, vcc, s39, v72
	s_nop 1
	v_addc_co_u32_e32 v5, vcc, 0, v73, vcc
	global_load_dword v88, v[4:5], off
	v_add_co_u32_e32 v4, vcc, s40, v72
	s_nop 1
	v_addc_co_u32_e32 v5, vcc, 0, v73, vcc
	global_load_dword v89, v[4:5], off
	v_add_co_u32_e32 v4, vcc, s41, v72
	s_nop 1
	v_addc_co_u32_e32 v5, vcc, 0, v73, vcc
	global_load_dword v94, v[4:5], off
	v_add_co_u32_e32 v4, vcc, s42, v72
	s_nop 1
	v_addc_co_u32_e32 v5, vcc, 0, v73, vcc
	global_load_dword v95, v[4:5], off
	v_add_co_u32_e32 v4, vcc, s43, v72
	s_nop 1
	v_addc_co_u32_e32 v5, vcc, 0, v73, vcc
	global_load_dword v78, v[4:5], off
	v_add_co_u32_e32 v4, vcc, s44, v72
	s_nop 1
	v_addc_co_u32_e32 v5, vcc, 0, v73, vcc
	global_load_dword v79, v[4:5], off
	v_add_co_u32_e32 v4, vcc, s45, v72
	s_nop 1
	v_addc_co_u32_e32 v5, vcc, 0, v73, vcc
	global_load_dword v74, v[4:5], off
	v_add_co_u32_e32 v4, vcc, s46, v72
	s_nop 1
	v_addc_co_u32_e32 v5, vcc, 0, v73, vcc
	global_load_dword v76, v[4:5], off
	s_branch .Lmods_ldone
; template <int ph> __device__ __forceinline__ void run_phase(const MArgs& a, unsigned char* lds, int tid, int lane, int wave, int G, int bx, int vcu) {
;     ...
;       for (int k0 = wave * 128; k0 < wave * 128 + 128; k0 += 16) { float wv[16];
; #pragma unroll
;         for (int q = 0; q < 16; ++q) wv[q] = W[(size_t)(k0 + q) * 6144];
; #pragma unroll
;         for (int q = 0; q < 16; ++q)
; #pragma unroll
;           for (int r = 0; r < 17; ++r) acc[r] += cond[r * 1024 + k0 + q] * wv[q]; }
.Lmods_dummy:
	global_load_dword v250, v[72:73], off
	v_add_co_u32_e32 v4, vcc, s29, v72
	s_nop 1
	v_addc_co_u32_e32 v5, vcc, 0, v73, vcc
	global_load_dword v250, v[4:5], off
	v_add_co_u32_e32 v4, vcc, s31, v72
	s_nop 1
	v_addc_co_u32_e32 v5, vcc, 0, v73, vcc
	global_load_dword v250, v[4:5], off
	v_add_co_u32_e32 v4, vcc, s34, v72
	s_nop 1
	v_addc_co_u32_e32 v5, vcc, 0, v73, vcc
	global_load_dword v250, v[4:5], off
	v_add_co_u32_e32 v4, vcc, s35, v72
	s_nop 1
	v_addc_co_u32_e32 v5, vcc, 0, v73, vcc
	global_load_dword v250, v[4:5], off
	v_add_co_u32_e32 v4, vcc, s36, v72
	s_nop 1
	v_addc_co_u32_e32 v5, vcc, 0, v73, vcc
	global_load_dword v250, v[4:5], off
	v_add_co_u32_e32 v4, vcc, s37, v72
	s_nop 1
	v_addc_co_u32_e32 v5, vcc, 0, v73, vcc
	global_load_dword v250, v[4:5], off
	v_add_co_u32_e32 v4, vcc, s38, v72
	s_nop 1
	v_addc_co_u32_e32 v5, vcc, 0, v73, vcc
	global_load_dword v250, v[4:5], off
	v_add_co_u32_e32 v4, vcc, s39, v72
	s_nop 1
	v_addc_co_u32_e32 v5, vcc, 0, v73, vcc
	global_load_dword v250, v[4:5], off
	v_add_co_u32_e32 v4, vcc, s40, v72
	s_nop 1
	v_addc_co_u32_e32 v5, vcc, 0, v73, vcc
	global_load_dword v250, v[4:5], off
	v_add_co_u32_e32 v4, vcc, s41, v72
	s_nop 1
	v_addc_co_u32_e32 v5, vcc, 0, v73, vcc
	global_load_dword v250, v[4:5], off
	v_add_co_u32_e32 v4, vcc, s42, v72
	s_nop 1
	v_addc_co_u32_e32 v5, vcc, 0, v73, vcc
	global_load_dword v250, v[4:5], off
	v_add_co_u32_e32 v4, vcc, s43, v72
	s_nop 1
	v_addc_co_u32_e32 v5, vcc, 0, v73, vcc
	global_load_dword v250, v[4:5], off
	v_add_co_u32_e32 v4, vcc, s44, v72
	s_nop 1
	v_addc_co_u32_e32 v5, vcc, 0, v73, vcc
	global_load_dword v250, v[4:5], off
	v_add_co_u32_e32 v4, vcc, s45, v72
	s_nop 1
	v_addc_co_u32_e32 v5, vcc, 0, v73, vcc
	global_load_dword v250, v[4:5], off
	v_add_co_u32_e32 v4, vcc, s46, v72
	s_nop 1
	v_addc_co_u32_e32 v5, vcc, 0, v73, vcc
	global_load_dword v250, v[4:5], off
.Lmods_ldone:
	s_add_i32 s50, s50, 1
	s_cmp_lt_u32 s50, 8
	s_cselect_b32 s48, s6, 0
	v_lshl_add_u64 v[72:73], v[72:73], 0, s[48:49]
	s_add_i32 s47, s30, 0x10000
	v_mov_b32_e32 v69, s30
	s_add_i32 s5, s5, 16
	v_mov_b32_e32 v4, s47
	ds_read_b128 v[4:7], v4
	s_add_i32 s47, s30, 0x10010
	s_waitcnt vmcnt(31) lgkmcnt(0)
	v_fmac_f32_e32 v1, v204, v4
	s_waitcnt vmcnt(30)
	v_fmac_f32_e32 v1, v206, v5
	s_waitcnt vmcnt(29)
	v_fmac_f32_e32 v1, v208, v6
	s_waitcnt vmcnt(28)
	v_fmac_f32_e32 v1, v210, v7
	ds_read_b128 v[4:7], v69
	ds_read_b128 v[112:115], v69 offset:16
	ds_read_b128 v[64:67], v69 offset:32
	ds_read_b128 v[52:55], v69 offset:48
	ds_read_b128 v[116:119], v69 offset:4112
	ds_read_b128 v[8:11], v69 offset:4096
	s_waitcnt lgkmcnt(5)
	v_mov_b32_e32 v12, v4
	v_mov_b32_e32 v4, v6
	s_waitcnt lgkmcnt(0)
	v_mov_b32_e32 v13, v8
	v_pk_fma_f32 v[2:3], v[204:205], v[12:13], v[2:3] op_sel_hi:[0,1,1]
	v_mov_b32_e32 v8, v5
	v_pk_fma_f32 v[2:3], v[206:207], v[8:9], v[2:3] op_sel_hi:[0,1,1]
	v_mov_b32_e32 v5, v10
	v_pk_fma_f32 v[2:3], v[208:209], v[4:5], v[2:3] op_sel_hi:[0,1,1]
	v_mov_b32_e32 v10, v7
	v_pk_fma_f32 v[2:3], v[210:211], v[10:11], v[2:3] op_sel_hi:[0,1,1]
	v_mov_b32_e32 v4, v112
	v_mov_b32_e32 v5, v116
	s_waitcnt vmcnt(27)
	v_pk_fma_f32 v[128:129], v[202:203], v[4:5], v[2:3] op_sel_hi:[0,1,1]
	ds_read_b128 v[56:59], v69 offset:8208
	ds_read_b128 v[60:63], v69 offset:12304
	ds_read_b128 v[2:5], v69 offset:8192
	ds_read_b128 v[6:9], v69 offset:12288
	v_mov_b32_e32 v116, v113
	s_waitcnt lgkmcnt(1)
	v_mov_b32_e32 v10, v2
	s_waitcnt lgkmcnt(0)
	v_mov_b32_e32 v11, v6
	v_pk_fma_f32 v[10:11], v[204:205], v[10:11], v[20:21] op_sel_hi:[0,1,1]
	v_mov_b32_e32 v6, v3
	v_pk_fma_f32 v[2:3], v[206:207], v[6:7], v[10:11] op_sel_hi:[0,1,1]
	v_mov_b32_e32 v6, v4
	v_mov_b32_e32 v7, v8
	v_pk_fma_f32 v[2:3], v[208:209], v[6:7], v[2:3] op_sel_hi:[0,1,1]
	v_mov_b32_e32 v8, v5
	v_pk_fma_f32 v[2:3], v[210:211], v[8:9], v[2:3] op_sel_hi:[0,1,1]
	v_mov_b32_e32 v4, v56
	v_mov_b32_e32 v5, v60
	v_pk_fma_f32 v[100:101], v[202:203], v[4:5], v[2:3] op_sel_hi:[0,1,1]
	ds_read_b128 v[44:47], v69 offset:16400
	ds_read_b128 v[48:51], v69 offset:20496
	ds_read_b128 v[2:5], v69 offset:16384
	ds_read_b128 v[6:9], v69 offset:20480
	v_mov_b32_e32 v60, v57
	s_waitcnt lgkmcnt(1)
	v_mov_b32_e32 v10, v2
	s_waitcnt lgkmcnt(0)
	v_mov_b32_e32 v11, v6
	v_pk_fma_f32 v[10:11], v[204:205], v[10:11], v[28:29] op_sel_hi:[0,1,1]
	v_mov_b32_e32 v6, v3
	v_pk_fma_f32 v[2:3], v[206:207], v[6:7], v[10:11] op_sel_hi:[0,1,1]
	v_mov_b32_e32 v6, v4
	v_mov_b32_e32 v7, v8
	v_pk_fma_f32 v[2:3], v[208:209], v[6:7], v[2:3] op_sel_hi:[0,1,1]
	v_mov_b32_e32 v8, v5
	v_pk_fma_f32 v[2:3], v[210:211], v[8:9], v[2:3] op_sel_hi:[0,1,1]
	v_mov_b32_e32 v4, v44
	v_mov_b32_e32 v5, v48
	v_pk_fma_f32 v[98:99], v[202:203], v[4:5], v[2:3] op_sel_hi:[0,1,1]
	ds_read_b128 v[36:39], v69 offset:24592
	ds_read_b128 v[40:43], v69 offset:28688
	ds_read_b128 v[2:5], v69 offset:24576
	ds_read_b128 v[6:9], v69 offset:28672
	s_waitcnt vmcnt(22)
	v_mov_b32_e32 v44, v189
	s_waitcnt vmcnt(20)
	v_mov_b32_e32 v56, v195
	v_mov_b32_e32 v48, v45
	s_waitcnt lgkmcnt(1)
	v_mov_b32_e32 v10, v2
	s_waitcnt lgkmcnt(0)
	v_mov_b32_e32 v11, v6
	v_pk_fma_f32 v[10:11], v[204:205], v[10:11], v[80:81] op_sel_hi:[0,1,1]
	v_mov_b32_e32 v6, v3
	v_pk_fma_f32 v[2:3], v[206:207], v[6:7], v[10:11] op_sel_hi:[0,1,1]
	v_mov_b32_e32 v6, v4
	v_mov_b32_e32 v7, v8
	v_pk_fma_f32 v[2:3], v[208:209], v[6:7], v[2:3] op_sel_hi:[0,1,1]
	v_mov_b32_e32 v8, v5
	v_pk_fma_f32 v[2:3], v[210:211], v[8:9], v[2:3] op_sel_hi:[0,1,1]
	v_mov_b32_e32 v4, v36
	v_mov_b32_e32 v5, v40
	v_pk_fma_f32 v[80:81], v[202:203], v[4:5], v[2:3] op_sel_hi:[0,1,1]
	ds_read_b128 v[28:31], v69 offset:32784
	ds_read_b128 v[32:35], v69 offset:36880
	ds_read_b128 v[2:5], v69 offset:32768
	ds_read_b128 v[6:9], v69 offset:36864
	s_waitcnt vmcnt(18)
; template <int ph> __device__ __forceinline__ void run_phase(const MArgs& a, unsigned char* lds, int tid, int lane, int wave, int G, int bx, int vcu) {
;     ...
;       for (int k0 = wave * 128; k0 < wave * 128 + 128; k0 += 16) { float wv[16];
; #pragma unroll
;         for (int q = 0; q < 16; ++q) wv[q] = W[(size_t)(k0 + q) * 6144];
; #pragma unroll
;         for (int q = 0; q < 16; ++q)
; #pragma unroll
;           for (int r = 0; r < 17; ++r) acc[r] += cond[r * 1024 + k0 + q] * wv[q]; }
	v_mov_b32_e32 v36, v179
	v_mov_b32_e32 v40, v37
	v_pk_fma_f32 v[40:41], v[190:191], v[40:41], v[80:81] op_sel_hi:[0,1,1]
	s_waitcnt lgkmcnt(1)
	v_mov_b32_e32 v10, v2
	s_waitcnt lgkmcnt(0)
	v_mov_b32_e32 v11, v6
	v_pk_fma_f32 v[10:11], v[204:205], v[10:11], v[82:83] op_sel_hi:[0,1,1]
	v_mov_b32_e32 v6, v3
	v_pk_fma_f32 v[2:3], v[206:207], v[6:7], v[10:11] op_sel_hi:[0,1,1]
	v_mov_b32_e32 v6, v4
	v_mov_b32_e32 v7, v8
	v_pk_fma_f32 v[2:3], v[208:209], v[6:7], v[2:3] op_sel_hi:[0,1,1]
	v_mov_b32_e32 v8, v5
	v_pk_fma_f32 v[2:3], v[210:211], v[8:9], v[2:3] op_sel_hi:[0,1,1]
	v_mov_b32_e32 v4, v28
	v_mov_b32_e32 v5, v32
	v_pk_fma_f32 v[82:83], v[202:203], v[4:5], v[2:3] op_sel_hi:[0,1,1]
	ds_read_b128 v[20:23], v69 offset:40976
	ds_read_b128 v[24:27], v69 offset:45072
	ds_read_b128 v[2:5], v69 offset:40960
	ds_read_b128 v[6:9], v69 offset:45056
	v_mov_b32_e32 v32, v29
	v_mov_b32_e32 v28, v58
	v_mov_b32_e32 v29, v62
	s_waitcnt lgkmcnt(1)
	v_mov_b32_e32 v10, v2
	s_waitcnt lgkmcnt(0)
	v_mov_b32_e32 v11, v6
	v_pk_fma_f32 v[10:11], v[204:205], v[10:11], v[84:85] op_sel_hi:[0,1,1]
	v_mov_b32_e32 v6, v3
	v_pk_fma_f32 v[2:3], v[206:207], v[6:7], v[10:11] op_sel_hi:[0,1,1]
	v_mov_b32_e32 v6, v4
	v_mov_b32_e32 v7, v8
	v_pk_fma_f32 v[2:3], v[208:209], v[6:7], v[2:3] op_sel_hi:[0,1,1]
	v_mov_b32_e32 v8, v5
	v_pk_fma_f32 v[2:3], v[210:211], v[8:9], v[2:3] op_sel_hi:[0,1,1]
	v_mov_b32_e32 v4, v20
	v_mov_b32_e32 v5, v24
	v_pk_fma_f32 v[84:85], v[202:203], v[4:5], v[2:3] op_sel_hi:[0,1,1]
	ds_read_b128 v[12:15], v69 offset:49168
	ds_read_b128 v[16:19], v69 offset:53264
	ds_read_b128 v[2:5], v69 offset:49152
	ds_read_b128 v[6:9], v69 offset:53248
	v_mov_b32_e32 v24, v21
	v_mov_b32_e32 v20, v64
	v_mov_b32_e32 v62, v59
	s_waitcnt lgkmcnt(1)
	v_mov_b32_e32 v10, v2
	s_waitcnt lgkmcnt(0)
	v_mov_b32_e32 v11, v6
	v_pk_fma_f32 v[10:11], v[204:205], v[10:11], v[86:87] op_sel_hi:[0,1,1]
	v_mov_b32_e32 v6, v3
	v_pk_fma_f32 v[2:3], v[206:207], v[6:7], v[10:11] op_sel_hi:[0,1,1]
	v_mov_b32_e32 v6, v4
	v_mov_b32_e32 v7, v8
	v_pk_fma_f32 v[2:3], v[208:209], v[6:7], v[2:3] op_sel_hi:[0,1,1]
	v_mov_b32_e32 v8, v5
	v_pk_fma_f32 v[2:3], v[210:211], v[8:9], v[2:3] op_sel_hi:[0,1,1]
	v_mov_b32_e32 v4, v12
	v_mov_b32_e32 v5, v16
	v_pk_fma_f32 v[86:87], v[202:203], v[4:5], v[2:3] op_sel_hi:[0,1,1]
	ds_read_b128 v[4:7], v69 offset:57360
	ds_read_b128 v[8:11], v69 offset:61456
	ds_read_b128 v[120:123], v69 offset:57344
	ds_read_b128 v[124:127], v69 offset:61440
	v_mov_b32_e32 v16, v13
	v_mov_b32_e32 v12, v114
	v_mov_b32_e32 v13, v118
	s_waitcnt lgkmcnt(1)
	v_mov_b32_e32 v2, v120
	s_waitcnt lgkmcnt(0)
	v_mov_b32_e32 v3, v124
	v_pk_fma_f32 v[2:3], v[204:205], v[2:3], v[96:97] op_sel_hi:[0,1,1]
	v_mov_b32_e32 v124, v121
	v_pk_fma_f32 v[2:3], v[206:207], v[124:125], v[2:3] op_sel_hi:[0,1,1]
	v_mov_b32_e32 v96, v122
	v_mov_b32_e32 v97, v126
	v_pk_fma_f32 v[2:3], v[208:209], v[96:97], v[2:3] op_sel_hi:[0,1,1]
	v_mov_b32_e32 v126, v123
	v_pk_fma_f32 v[2:3], v[210:211], v[126:127], v[2:3] op_sel_hi:[0,1,1]
	v_mov_b32_e32 v96, v4
	v_mov_b32_e32 v97, v8
	v_pk_fma_f32 v[96:97], v[202:203], v[96:97], v[2:3] op_sel_hi:[0,1,1]
	v_mov_b32_e32 v2, s47
	v_mov_b32_e32 v8, v5
	ds_read_b128 v[2:5], v2
	v_mov_b32_e32 v203, v190
	s_add_i32 s47, s30, 0x10020
	v_mov_b32_e32 v118, v115
	v_pk_fma_f32 v[32:33], v[190:191], v[32:33], v[82:83] op_sel_hi:[0,1,1]
	s_waitcnt lgkmcnt(0)
	v_pk_mul_f32 v[2:3], v[202:203], v[2:3]
	ds_read_b128 v[202:205], v69 offset:4128
	v_add_f32_e32 v1, v1, v2
	v_add_f32_e32 v1, v1, v3
	v_pk_mul_f32 v[2:3], v[192:193], v[4:5]
	v_pk_fma_f32 v[24:25], v[190:191], v[24:25], v[84:85] op_sel_hi:[0,1,1]
	v_add_f32_e32 v1, v1, v2
	v_mov_b32_e32 v2, s47
	v_add_f32_e32 v1, v1, v3
	ds_read_b128 v[2:5], v2
	s_add_i32 s47, s30, 0x10030
	s_waitcnt lgkmcnt(1)
	v_mov_b32_e32 v21, v202
	v_mov_b32_e32 v202, v65
	v_pk_fma_f32 v[16:17], v[190:191], v[16:17], v[86:87] op_sel_hi:[0,1,1]
	s_waitcnt lgkmcnt(0)
	v_pk_mul_f32 v[2:3], v[188:189], v[2:3]
	v_pk_fma_f32 v[8:9], v[190:191], v[8:9], v[96:97] op_sel_hi:[0,1,1]
	v_add_f32_e32 v1, v1, v2
	v_add_f32_e32 v1, v1, v3
	v_pk_mul_f32 v[2:3], v[194:195], v[4:5]
	s_add_i32 s30, s30, 64
	v_add_f32_e32 v1, v1, v2
	v_mov_b32_e32 v2, s47
	v_add_f32_e32 v1, v1, v3
	ds_read_b128 v[2:5], v2
	s_cmp_ge_u32 s5, s28
	s_waitcnt lgkmcnt(0)
	v_pk_mul_f32 v[2:3], v[178:179], v[2:3]
	s_nop 0
	v_add_f32_e32 v1, v1, v2
	v_add_f32_e32 v1, v1, v3
	v_pk_fma_f32 v[2:3], v[190:191], v[116:117], v[128:129] op_sel_hi:[0,1,1]
	v_pk_fma_f32 v[2:3], v[192:193], v[12:13], v[2:3] op_sel_hi:[0,1,1]
	v_mov_b32_e32 v12, v193
	v_pk_fma_f32 v[2:3], v[12:13], v[118:119], v[2:3] op_sel_hi:[0,1,1]
	v_pk_fma_f32 v[2:3], v[188:189], v[20:21], v[2:3] op_sel_hi:[0,1,1]
	v_mov_b32_e32 v20, v66
	v_mov_b32_e32 v21, v204
	v_mov_b32_e32 v204, v67
	ds_read_b128 v[64:67], v69 offset:4144
	v_pk_fma_f32 v[2:3], v[44:45], v[202:203], v[2:3] op_sel_hi:[0,1,1]
	v_pk_fma_f32 v[2:3], v[194:195], v[20:21], v[2:3] op_sel_hi:[0,1,1]
	v_pk_fma_f32 v[2:3], v[56:57], v[204:205], v[2:3] op_sel_hi:[0,1,1]
	v_mov_b32_e32 v20, v52
	s_waitcnt lgkmcnt(0)
	v_mov_b32_e32 v21, v64
	v_pk_fma_f32 v[2:3], v[178:179], v[20:21], v[2:3] op_sel_hi:[0,1,1]
	v_mov_b32_e32 v64, v53
	v_pk_fma_f32 v[2:3], v[36:37], v[64:65], v[2:3] op_sel_hi:[0,1,1]
	v_mov_b32_e32 v20, v54
	v_mov_b32_e32 v21, v66
	s_waitcnt vmcnt(17)
	v_pk_fma_f32 v[2:3], v[174:175], v[20:21], v[2:3] op_sel_hi:[0,1,1]
	v_mov_b32_e32 v66, v55
	v_pk_fma_f32 v[20:21], v[190:191], v[60:61], v[100:101] op_sel_hi:[0,1,1]
	ds_read_b128 v[52:55], v69 offset:8224
	ds_read_b128 v[58:61], v69 offset:12320
	v_pk_fma_f32 v[20:21], v[192:193], v[28:29], v[20:21] op_sel_hi:[0,1,1]
	v_pk_fma_f32 v[20:21], v[12:13], v[62:63], v[20:21] op_sel_hi:[0,1,1]
	s_waitcnt vmcnt(16)
; template <int ph> __device__ __forceinline__ void run_phase(const MArgs& a, unsigned char* lds, int tid, int lane, int wave, int G, int bx, int vcu) {
;     ...
;         for (int q = 0; q < 16; ++q)
; #pragma unroll
;           for (int r = 0; r < 17; ++r) acc[r] += cond[r * 1024 + k0 + q] * wv[q]; }
	v_pk_fma_f32 v[2:3], v[176:177], v[66:67], v[2:3] op_sel_hi:[0,1,1]
	s_waitcnt lgkmcnt(1)
	v_mov_b32_e32 v28, v52
	s_waitcnt lgkmcnt(0)
	v_mov_b32_e32 v29, v58
	v_pk_fma_f32 v[20:21], v[188:189], v[28:29], v[20:21] op_sel_hi:[0,1,1]
	v_mov_b32_e32 v58, v53
	v_pk_fma_f32 v[20:21], v[44:45], v[58:59], v[20:21] op_sel_hi:[0,1,1]
	v_mov_b32_e32 v28, v54
	v_mov_b32_e32 v29, v60
	v_pk_fma_f32 v[20:21], v[194:195], v[28:29], v[20:21] op_sel_hi:[0,1,1]
	v_mov_b32_e32 v60, v55
	v_pk_fma_f32 v[20:21], v[56:57], v[60:61], v[20:21] op_sel_hi:[0,1,1]
	ds_read_b128 v[52:55], v69 offset:8240
	ds_read_b128 v[58:61], v69 offset:12336
	s_waitcnt lgkmcnt(1)
	v_mov_b32_e32 v28, v52
	s_waitcnt lgkmcnt(0)
	v_mov_b32_e32 v29, v58
	v_pk_fma_f32 v[20:21], v[178:179], v[28:29], v[20:21] op_sel_hi:[0,1,1]
	v_mov_b32_e32 v58, v53
	v_pk_fma_f32 v[20:21], v[36:37], v[58:59], v[20:21] op_sel_hi:[0,1,1]
	v_mov_b32_e32 v28, v54
	v_mov_b32_e32 v29, v60
	v_pk_fma_f32 v[20:21], v[174:175], v[28:29], v[20:21] op_sel_hi:[0,1,1]
	v_pk_fma_f32 v[28:29], v[190:191], v[48:49], v[98:99] op_sel_hi:[0,1,1]
	v_mov_b32_e32 v48, v46
	v_mov_b32_e32 v49, v50
	v_pk_fma_f32 v[28:29], v[192:193], v[48:49], v[28:29] op_sel_hi:[0,1,1]
	v_mov_b32_e32 v50, v47
	v_pk_fma_f32 v[28:29], v[12:13], v[50:51], v[28:29] op_sel_hi:[0,1,1]
	ds_read_b128 v[46:49], v69 offset:16416
	ds_read_b128 v[50:53], v69 offset:20512
	v_mov_b32_e32 v60, v55
	v_pk_fma_f32 v[20:21], v[176:177], v[60:61], v[20:21] op_sel_hi:[0,1,1]
	s_waitcnt lgkmcnt(1)
	v_mov_b32_e32 v54, v46
	s_waitcnt lgkmcnt(0)
	v_mov_b32_e32 v55, v50
	v_pk_fma_f32 v[28:29], v[188:189], v[54:55], v[28:29] op_sel_hi:[0,1,1]
	v_mov_b32_e32 v50, v47
	v_pk_fma_f32 v[28:29], v[44:45], v[50:51], v[28:29] op_sel_hi:[0,1,1]
	v_mov_b32_e32 v46, v48
	v_mov_b32_e32 v47, v52
	v_pk_fma_f32 v[28:29], v[194:195], v[46:47], v[28:29] op_sel_hi:[0,1,1]
	v_mov_b32_e32 v52, v49
	v_pk_fma_f32 v[28:29], v[56:57], v[52:53], v[28:29] op_sel_hi:[0,1,1]
	ds_read_b128 v[46:49], v69 offset:16432
	ds_read_b128 v[50:53], v69 offset:20528
	s_waitcnt lgkmcnt(1)
	v_mov_b32_e32 v54, v46
	s_waitcnt lgkmcnt(0)
	v_mov_b32_e32 v55, v50
	v_pk_fma_f32 v[28:29], v[178:179], v[54:55], v[28:29] op_sel_hi:[0,1,1]
	v_mov_b32_e32 v50, v47
	v_pk_fma_f32 v[28:29], v[36:37], v[50:51], v[28:29] op_sel_hi:[0,1,1]
	v_mov_b32_e32 v46, v48
	v_mov_b32_e32 v47, v52
	v_pk_fma_f32 v[28:29], v[174:175], v[46:47], v[28:29] op_sel_hi:[0,1,1]
	v_mov_b32_e32 v46, v38
	v_mov_b32_e32 v47, v42
	v_pk_fma_f32 v[40:41], v[192:193], v[46:47], v[40:41] op_sel_hi:[0,1,1]
	v_mov_b32_e32 v42, v39
	v_mov_b32_e32 v52, v49
	v_pk_fma_f32 v[42:43], v[12:13], v[42:43], v[40:41] op_sel_hi:[0,1,1]
	ds_read_b128 v[38:41], v69 offset:24608
	ds_read_b128 v[46:49], v69 offset:28704
	v_pk_fma_f32 v[28:29], v[176:177], v[52:53], v[28:29] op_sel_hi:[0,1,1]
	s_waitcnt lgkmcnt(1)
	v_mov_b32_e32 v50, v38
	s_waitcnt lgkmcnt(0)
	v_mov_b32_e32 v51, v46
	v_pk_fma_f32 v[42:43], v[188:189], v[50:51], v[42:43] op_sel_hi:[0,1,1]
	v_mov_b32_e32 v46, v39
	v_pk_fma_f32 v[38:39], v[44:45], v[46:47], v[42:43] op_sel_hi:[0,1,1]
	v_mov_b32_e32 v42, v40
	v_mov_b32_e32 v43, v48
	v_pk_fma_f32 v[38:39], v[194:195], v[42:43], v[38:39] op_sel_hi:[0,1,1]
	v_mov_b32_e32 v48, v41
	v_pk_fma_f32 v[42:43], v[56:57], v[48:49], v[38:39] op_sel_hi:[0,1,1]
	ds_read_b128 v[38:41], v69 offset:24624
	ds_read_b128 v[46:49], v69 offset:28720
	s_waitcnt lgkmcnt(1)
	v_mov_b32_e32 v50, v38
	s_waitcnt lgkmcnt(0)
	v_mov_b32_e32 v51, v46
	v_pk_fma_f32 v[42:43], v[178:179], v[50:51], v[42:43] op_sel_hi:[0,1,1]
	v_mov_b32_e32 v46, v39
	v_pk_fma_f32 v[38:39], v[36:37], v[46:47], v[42:43] op_sel_hi:[0,1,1]
	v_mov_b32_e32 v42, v40
	v_mov_b32_e32 v43, v48
	v_pk_fma_f32 v[38:39], v[174:175], v[42:43], v[38:39] op_sel_hi:[0,1,1]
	v_mov_b32_e32 v48, v41
	v_pk_fma_f32 v[80:81], v[176:177], v[48:49], v[38:39] op_sel_hi:[0,1,1]
	v_mov_b32_e32 v38, v30
	v_mov_b32_e32 v39, v34
	v_pk_fma_f32 v[32:33], v[192:193], v[38:39], v[32:33] op_sel_hi:[0,1,1]
	v_mov_b32_e32 v34, v31
	v_pk_fma_f32 v[34:35], v[12:13], v[34:35], v[32:33] op_sel_hi:[0,1,1]
	ds_read_b128 v[30:33], v69 offset:32800
	ds_read_b128 v[38:41], v69 offset:36896
	s_waitcnt lgkmcnt(1)
	v_mov_b32_e32 v42, v30
	s_waitcnt lgkmcnt(0)
	v_mov_b32_e32 v43, v38
	v_pk_fma_f32 v[34:35], v[188:189], v[42:43], v[34:35] op_sel_hi:[0,1,1]
	v_mov_b32_e32 v38, v31
	v_pk_fma_f32 v[30:31], v[44:45], v[38:39], v[34:35] op_sel_hi:[0,1,1]
	v_mov_b32_e32 v34, v32
	v_mov_b32_e32 v35, v40
	v_pk_fma_f32 v[30:31], v[194:195], v[34:35], v[30:31] op_sel_hi:[0,1,1]
	v_mov_b32_e32 v40, v33
	v_pk_fma_f32 v[34:35], v[56:57], v[40:41], v[30:31] op_sel_hi:[0,1,1]
	ds_read_b128 v[30:33], v69 offset:32816
	ds_read_b128 v[38:41], v69 offset:36912
	s_waitcnt lgkmcnt(1)
	v_mov_b32_e32 v42, v30
	s_waitcnt lgkmcnt(0)
	v_mov_b32_e32 v43, v38
	v_pk_fma_f32 v[34:35], v[178:179], v[42:43], v[34:35] op_sel_hi:[0,1,1]
	v_mov_b32_e32 v38, v31
	v_pk_fma_f32 v[30:31], v[36:37], v[38:39], v[34:35] op_sel_hi:[0,1,1]
	v_mov_b32_e32 v34, v32
	v_mov_b32_e32 v35, v40
	v_pk_fma_f32 v[30:31], v[174:175], v[34:35], v[30:31] op_sel_hi:[0,1,1]
	v_mov_b32_e32 v40, v33
	v_pk_fma_f32 v[82:83], v[176:177], v[40:41], v[30:31] op_sel_hi:[0,1,1]
	v_mov_b32_e32 v30, v22
	v_mov_b32_e32 v31, v26
	v_pk_fma_f32 v[24:25], v[192:193], v[30:31], v[24:25] op_sel_hi:[0,1,1]
	v_mov_b32_e32 v26, v23
	v_pk_fma_f32 v[26:27], v[12:13], v[26:27], v[24:25] op_sel_hi:[0,1,1]
	ds_read_b128 v[22:25], v69 offset:40992
	ds_read_b128 v[30:33], v69 offset:45088
	s_waitcnt lgkmcnt(1)
; template <int ph> __device__ __forceinline__ void run_phase(const MArgs& a, unsigned char* lds, int tid, int lane, int wave, int G, int bx, int vcu) {
;     ...
;       for (int k0 = wave * 128; k0 < wave * 128 + 128; k0 += 16) { float wv[16];
; #pragma unroll
;         for (int q = 0; q < 16; ++q) wv[q] = W[(size_t)(k0 + q) * 6144];
; #pragma unroll
;         for (int q = 0; q < 16; ++q)
; #pragma unroll
;           for (int r = 0; r < 17; ++r) acc[r] += cond[r * 1024 + k0 + q] * wv[q]; }
; #pragma unroll
;       for (int r = 0; r < 17; ++r) red[(wave * 17 + r) * 64 + lane] = acc[r];
;       __syncthreads();
;       for (int i = tid; i < 17 * 64; i += NWAVES * 64) { const int r = i >> 6, c = i & 63; float s = a.in[5][l * 6144 + cc * 64 + c];
; #pragma unroll
;         for (int w = 0; w < 8; ++w) s += red[(w * 17 + r) * 64 + c];
	v_mov_b32_e32 v34, v22
	s_waitcnt lgkmcnt(0)
	v_mov_b32_e32 v35, v30
	v_pk_fma_f32 v[26:27], v[188:189], v[34:35], v[26:27] op_sel_hi:[0,1,1]
	v_mov_b32_e32 v30, v23
	v_pk_fma_f32 v[22:23], v[44:45], v[30:31], v[26:27] op_sel_hi:[0,1,1]
	v_mov_b32_e32 v26, v24
	v_mov_b32_e32 v27, v32
	v_pk_fma_f32 v[22:23], v[194:195], v[26:27], v[22:23] op_sel_hi:[0,1,1]
	v_mov_b32_e32 v32, v25
	v_pk_fma_f32 v[26:27], v[56:57], v[32:33], v[22:23] op_sel_hi:[0,1,1]
	ds_read_b128 v[22:25], v69 offset:41008
	ds_read_b128 v[30:33], v69 offset:45104
	s_waitcnt lgkmcnt(1)
	v_mov_b32_e32 v34, v22
	s_waitcnt lgkmcnt(0)
	v_mov_b32_e32 v35, v30
	v_pk_fma_f32 v[26:27], v[178:179], v[34:35], v[26:27] op_sel_hi:[0,1,1]
	v_mov_b32_e32 v30, v23
	v_pk_fma_f32 v[22:23], v[36:37], v[30:31], v[26:27] op_sel_hi:[0,1,1]
	v_mov_b32_e32 v26, v24
	v_mov_b32_e32 v27, v32
	v_pk_fma_f32 v[22:23], v[174:175], v[26:27], v[22:23] op_sel_hi:[0,1,1]
	v_mov_b32_e32 v32, v25
	v_pk_fma_f32 v[84:85], v[176:177], v[32:33], v[22:23] op_sel_hi:[0,1,1]
	v_mov_b32_e32 v22, v14
	v_mov_b32_e32 v23, v18
	v_pk_fma_f32 v[16:17], v[192:193], v[22:23], v[16:17] op_sel_hi:[0,1,1]
	v_mov_b32_e32 v18, v15
	v_pk_fma_f32 v[18:19], v[12:13], v[18:19], v[16:17] op_sel_hi:[0,1,1]
	ds_read_b128 v[14:17], v69 offset:49184
	ds_read_b128 v[22:25], v69 offset:53280
	s_waitcnt lgkmcnt(1)
	v_mov_b32_e32 v26, v14
	s_waitcnt lgkmcnt(0)
	v_mov_b32_e32 v27, v22
	v_pk_fma_f32 v[18:19], v[188:189], v[26:27], v[18:19] op_sel_hi:[0,1,1]
	v_mov_b32_e32 v22, v15
	v_pk_fma_f32 v[14:15], v[44:45], v[22:23], v[18:19] op_sel_hi:[0,1,1]
	v_mov_b32_e32 v18, v16
	v_mov_b32_e32 v19, v24
	v_pk_fma_f32 v[14:15], v[194:195], v[18:19], v[14:15] op_sel_hi:[0,1,1]
	v_mov_b32_e32 v24, v17
	v_pk_fma_f32 v[18:19], v[56:57], v[24:25], v[14:15] op_sel_hi:[0,1,1]
	ds_read_b128 v[14:17], v69 offset:49200
	ds_read_b128 v[22:25], v69 offset:53296
	s_waitcnt lgkmcnt(1)
	v_mov_b32_e32 v26, v14
	s_waitcnt lgkmcnt(0)
	v_mov_b32_e32 v27, v22
	v_pk_fma_f32 v[18:19], v[178:179], v[26:27], v[18:19] op_sel_hi:[0,1,1]
	v_mov_b32_e32 v22, v15
	v_pk_fma_f32 v[14:15], v[36:37], v[22:23], v[18:19] op_sel_hi:[0,1,1]
	v_mov_b32_e32 v18, v16
	v_mov_b32_e32 v19, v24
	v_pk_fma_f32 v[14:15], v[174:175], v[18:19], v[14:15] op_sel_hi:[0,1,1]
	v_mov_b32_e32 v24, v17
	v_pk_fma_f32 v[86:87], v[176:177], v[24:25], v[14:15] op_sel_hi:[0,1,1]
	v_mov_b32_e32 v14, v6
	v_mov_b32_e32 v15, v10
	v_pk_fma_f32 v[8:9], v[192:193], v[14:15], v[8:9] op_sel_hi:[0,1,1]
	v_mov_b32_e32 v10, v7
	v_pk_fma_f32 v[14:15], v[12:13], v[10:11], v[8:9] op_sel_hi:[0,1,1]
	ds_read_b128 v[6:9], v69 offset:57376
	ds_read_b128 v[10:13], v69 offset:61472
	s_waitcnt lgkmcnt(1)
	v_mov_b32_e32 v16, v6
	s_waitcnt lgkmcnt(0)
	v_mov_b32_e32 v17, v10
	v_pk_fma_f32 v[14:15], v[188:189], v[16:17], v[14:15] op_sel_hi:[0,1,1]
	v_mov_b32_e32 v10, v7
	v_pk_fma_f32 v[6:7], v[44:45], v[10:11], v[14:15] op_sel_hi:[0,1,1]
	v_mov_b32_e32 v10, v8
	v_mov_b32_e32 v11, v12
	v_pk_fma_f32 v[6:7], v[194:195], v[10:11], v[6:7] op_sel_hi:[0,1,1]
	v_mov_b32_e32 v12, v9
	v_pk_fma_f32 v[14:15], v[56:57], v[12:13], v[6:7] op_sel_hi:[0,1,1]
	ds_read_b128 v[6:9], v69 offset:57392
	ds_read_b128 v[10:13], v69 offset:61488
	s_waitcnt lgkmcnt(1)
	v_mov_b32_e32 v16, v6
	s_waitcnt lgkmcnt(0)
	v_mov_b32_e32 v17, v10
	v_pk_fma_f32 v[14:15], v[178:179], v[16:17], v[14:15] op_sel_hi:[0,1,1]
	v_mov_b32_e32 v10, v7
	v_pk_fma_f32 v[6:7], v[36:37], v[10:11], v[14:15] op_sel_hi:[0,1,1]
	v_mov_b32_e32 v10, v8
	v_mov_b32_e32 v11, v12
	v_pk_fma_f32 v[6:7], v[174:175], v[10:11], v[6:7] op_sel_hi:[0,1,1]
	v_mov_b32_e32 v175, v176
	v_pk_mul_f32 v[4:5], v[174:175], v[4:5]
	v_mov_b32_e32 v12, v9
	v_add_f32_e32 v1, v1, v4
	v_pk_fma_f32 v[96:97], v[176:177], v[12:13], v[6:7] op_sel_hi:[0,1,1]
	v_add_f32_e32 v1, v1, v5
	s_cbranch_scc0 .LBB0_24
	s_add_i32 s5, 0, 0x11000
	s_mul_i32 s6, s93, 0x1100
	s_add_i32 s6, s6, s5
	v_add_u32_e32 v6, s6, v70
	s_mul_i32 s6, s3, 0x1800
	s_add_i32 s6, s6, s4
	s_mul_hi_i32 s4, s3, 0x66000
	s_mul_i32 s3, s3, 0x66000
	ds_write2st64_b32 v6, v2, v3 offset1:1
	ds_write2st64_b32 v6, v20, v21 offset0:2 offset1:3
	ds_write2st64_b32 v6, v28, v29 offset0:4 offset1:5
	ds_write2st64_b32 v6, v80, v81 offset0:6 offset1:7
	ds_write2st64_b32 v6, v82, v83 offset0:8 offset1:9
	ds_write2st64_b32 v6, v84, v85 offset0:10 offset1:11
	ds_write2st64_b32 v6, v86, v87 offset0:12 offset1:13
	ds_write2st64_b32 v6, v96, v97 offset0:14 offset1:15
	ds_write_b32 v6, v1 offset:4096
	v_or_b32_e32 v2, s6, v254
	s_add_u32 s0, s0, s3
	v_mov_b32_e32 v4, s62
	v_mov_b32_e32 v5, s63
	v_ashrrev_i32_e32 v3, 31, v2
	s_addc_u32 s1, s1, s4
	v_lshl_add_u64 v[2:3], v[2:3], 2, v[4:5]
	v_lshrrev_b32_e32 v6, 6, v0
	s_movk_i32 s3, 0x6000
	v_mov_b64_e32 v[4:5], s[0:1]
	v_mad_u64_u32 v[4:5], s[0:1], v6, s3, v[4:5]
	v_lshl_add_u64 v[4:5], v[4:5], 0, v[70:71]
	v_lshl_add_u64 v[4:5], s[26:27], 0, v[4:5]
	s_mov_b64 s[0:1], 0x100000
	v_lshl_add_u64 v[4:5], v[4:5], 0, s[0:1]
	s_movk_i32 s0, 0x700
	v_and_or_b32 v6, v68, s0, v70
	v_or_b32_e32 v1, 0xfffffe00, v0
	v_add_u32_e32 v6, s5, v6
	s_mov_b64 s[0:1], 0
	s_mov_b64 s[4:5], 0x30000
	s_movk_i32 s3, 0x23f
	s_waitcnt lgkmcnt(0)
	s_barrier
